# in-proj GEMM: K order rotated by (tm&7) stages per row-block group, like the LN2 rotation
# speedup vs baseline: 1.0013x; 1.0013x over previous
.Lip_nodep:
	s_and_b32 s65, s13, 7
	s_sub_i32 s64, 13, s65
	s_lshl_b32 s65, s65, 7
	s_lshl_b32 s26, s13, 8
	s_ashr_i32 s27, s26, 31
	s_lshl_b64 s[34:35], s[26:27], 11
	s_or_b32 s34, s34, s65
	s_mov_b32 m0, s11
	v_lshl_add_u64 v[2:3], v[106:107], 0, s[34:35]
	s_lshl_b32 s22, s6, 7
	global_load_lds_dwordx4 v[2:3], off sc1
	v_lshl_add_u64 v[6:7], v[2:3], 0, s[30:31]
	s_add_i32 m0, s11, 0x400
	s_ashr_i32 s23, s22, 31
	global_load_lds_dwordx4 v[6:7], off sc1
	v_lshl_add_u64 v[6:7], v[2:3], 0, s[24:25]
	s_add_i32 m0, s11, 0x800
	s_mov_b64 s[16:17], 0xc000
	s_lshl_b64 s[36:37], s[22:23], 11
	s_or_b32 s36, s36, s65
	global_load_lds_dwordx4 v[6:7], off sc1
	v_lshl_add_u64 v[6:7], v[2:3], 0, s[16:17]
	s_add_i32 m0, s11, 0xc00
	v_lshl_add_u64 v[4:5], v[108:109], 0, s[36:37]
	global_load_lds_dwordx4 v[6:7], off sc1
	s_add_i32 m0, s12, 0x8000
	v_lshl_add_u64 v[6:7], v[4:5], 0, s[30:31]
	global_load_lds_dwordx4 v[4:5], off sc1
	s_add_i32 m0, s12, 0x8400
	s_mov_b64 s[16:17], 0x4080
	global_load_lds_dwordx4 v[6:7], off sc1
	v_lshl_add_u64 v[6:7], v[2:3], 0, s[2:3]
	s_add_i32 m0, s11, 0xc000
	s_mov_b64 s[46:47], 0x8080
	global_load_lds_dwordx4 v[6:7], off sc1
	v_lshl_add_u64 v[6:7], v[2:3], 0, s[16:17]
	s_add_i32 m0, s11, 0xc400
	s_mov_b64 s[48:49], 0x8100
	global_load_lds_dwordx4 v[6:7], off sc1
	v_lshl_add_u64 v[6:7], v[2:3], 0, s[46:47]
	s_add_i32 m0, s11, 0xc800
	s_mov_b64 s[46:47], 0xc080
	global_load_lds_dwordx4 v[6:7], off sc1
	v_lshl_add_u64 v[6:7], v[2:3], 0, s[46:47]
	s_add_i32 m0, s11, 0xcc00
	s_mov_b64 s[46:47], 0x4100
	global_load_lds_dwordx4 v[6:7], off sc1
	v_lshl_add_u64 v[6:7], v[4:5], 0, s[2:3]
	s_add_i32 m0, s12, 0x14000
	v_add_u32_e32 v117, v123, v124
	global_load_lds_dwordx4 v[6:7], off sc1
	v_lshl_add_u64 v[6:7], v[4:5], 0, s[16:17]
	s_add_i32 m0, s12, 0x14400
	s_mov_b64 s[16:17], 0x100
	global_load_lds_dwordx4 v[6:7], off sc1
	v_lshl_add_u64 v[6:7], v[2:3], 0, s[16:17]
	s_add_i32 m0, s11, 0x18000
	v_add_u32_e32 v221, v125, v124
	global_load_lds_dwordx4 v[6:7], off sc1
	v_lshl_add_u64 v[6:7], v[2:3], 0, s[46:47]
	s_add_i32 m0, s11, 0x18400
	v_mov_b32_e32 v34, 0
	global_load_lds_dwordx4 v[6:7], off sc1
	v_lshl_add_u64 v[6:7], v[2:3], 0, s[48:49]
	s_add_i32 m0, s11, 0x18800
	s_mov_b64 s[48:49], 0xc100
	global_load_lds_dwordx4 v[6:7], off sc1
	v_lshl_add_u64 v[2:3], v[2:3], 0, s[48:49]
	s_add_i32 m0, s11, 0x18c00
	v_lshl_add_u64 v[118:119], v[104:105], 0, s[34:35]
	global_load_lds_dwordx4 v[2:3], off sc1
	v_lshl_add_u64 v[2:3], v[4:5], 0, s[16:17]
	s_add_i32 m0, s12, 0x20000
	v_lshl_add_u64 v[120:121], v[114:115], 0, s[36:37]
	global_load_lds_dwordx4 v[2:3], off sc1
	v_lshl_add_u64 v[2:3], v[4:5], 0, s[46:47]
	s_add_i32 m0, s12, 0x20400
	s_mov_b32 s6, -1
	global_load_lds_dwordx4 v[2:3], off sc1
	s_waitcnt vmcnt(12)
	s_waitcnt lgkmcnt(0)
	s_barrier
	ds_read_b128 v[30:33], v117
	ds_read_b128 v[26:29], v221 offset:2048
	ds_read_b128 v[14:17], v221 offset:4096
	ds_read_b128 v[2:5], v221 offset:6144
	ds_read_b128 v[22:25], v210 offset:32768
	ds_read_b128 v[18:21], v212 offset:34816
	ds_read_b128 v[10:13], v212 offset:36864
	ds_read_b128 v[6:9], v212 offset:38912
	s_mov_b32 s13, 0
	s_mov_b32 s14, 1
	s_mov_b32 s19, 0
	v_mov_b32_e32 v35, v34
	v_mov_b32_e32 v36, v34
	v_mov_b32_e32 v37, v34
	v_mov_b32_e32 v42, v34
	v_mov_b32_e32 v43, v34
	v_mov_b32_e32 v44, v34
	v_mov_b32_e32 v45, v34
	v_mov_b32_e32 v46, v34
	v_mov_b32_e32 v47, v34
	v_mov_b32_e32 v48, v34
	v_mov_b32_e32 v49, v34
	v_mov_b32_e32 v50, v34
	v_mov_b32_e32 v51, v34
	v_mov_b32_e32 v52, v34
	v_mov_b32_e32 v53, v34
	v_mov_b32_e32 v54, v34
	v_mov_b32_e32 v55, v34
	v_mov_b32_e32 v56, v34
	v_mov_b32_e32 v57, v34
	v_mov_b32_e32 v58, v34
	v_mov_b32_e32 v59, v34
	v_mov_b32_e32 v60, v34
	v_mov_b32_e32 v61, v34
	v_mov_b32_e32 v62, v34
	v_mov_b32_e32 v63, v34
	v_mov_b32_e32 v64, v34
	v_mov_b32_e32 v65, v34
	v_mov_b32_e32 v66, v34
	v_mov_b32_e32 v67, v34
	v_mov_b32_e32 v68, v34
	v_mov_b32_e32 v69, v34
	v_mov_b32_e32 v70, v34
	v_mov_b32_e32 v71, v34
	v_mov_b32_e32 v72, v34
	v_mov_b32_e32 v73, v34
	v_mov_b32_e32 v74, v34
	v_mov_b32_e32 v75, v34
	v_mov_b32_e32 v76, v34
	v_mov_b32_e32 v77, v34
	v_mov_b32_e32 v78, v34
	v_mov_b32_e32 v79, v34
	v_mov_b32_e32 v80, v34
	v_mov_b32_e32 v81, v34
	v_mov_b32_e32 v82, v34
	v_mov_b32_e32 v83, v34
	v_mov_b32_e32 v84, v34
	v_mov_b32_e32 v85, v34
	v_mov_b32_e32 v94, v34
	v_mov_b32_e32 v95, v34
	v_mov_b32_e32 v96, v34
	v_mov_b32_e32 v97, v34
	v_mov_b32_e32 v86, v34
	v_mov_b32_e32 v87, v34
	v_mov_b32_e32 v88, v34
	v_mov_b32_e32 v89, v34
	v_mov_b32_e32 v90, v34
	v_mov_b32_e32 v91, v34
	v_mov_b32_e32 v92, v34
	v_mov_b32_e32 v93, v34
	v_mov_b32_e32 v38, v34
	v_mov_b32_e32 v39, v34
	v_mov_b32_e32 v40, v34
	v_mov_b32_e32 v41, v34
.LBB0_347:
	s_mul_hi_u32 s20, s19, 0xaaaaaaab
	s_lshr_b32 s20, s20, 1
	s_mul_i32 s20, s20, 0x24000
	s_waitcnt lgkmcnt(0)
	v_mfma_f32_16x16x32_bf16 v[82:85], v[26:29], v[22:25], v[82:85]
	v_add_u32_e32 v191, s13, v122
	s_mul_hi_u32 s23, s14, 0xaaaaaaab
	s_lshr_b32 s23, s23, 1
	v_mfma_f32_16x16x32_bf16 v[78:81], v[26:29], v[18:21], v[78:81]
	s_mul_i32 s23, s23, 0x24000
	v_subrev_u32_e32 v250, s23, v182
	v_subrev_u32_e32 v251, s23, v201
	v_mfma_f32_16x16x32_bf16 v[74:77], v[26:29], v[10:13], v[74:77]
	v_subrev_u32_e32 v252, s23, v202
	v_mfma_f32_16x16x32_bf16 v[70:73], v[26:29], v[6:9], v[70:73]
	v_subrev_u32_e32 v26, s20, v181
	v_mfma_f32_16x16x32_bf16 v[66:69], v[14:17], v[22:25], v[66:69]
	v_mfma_f32_16x16x32_bf16 v[62:65], v[14:17], v[18:21], v[62:65]
	v_mfma_f32_16x16x32_bf16 v[58:61], v[14:17], v[10:13], v[58:61]
	v_mfma_f32_16x16x32_bf16 v[54:57], v[14:17], v[6:9], v[54:57]
	v_subrev_u32_e32 v14, s20, v203
	v_add_u32_e32 v16, v191, v26
	v_add_u32_e32 v14, v191, v14
	v_mfma_f32_16x16x32_bf16 v[38:41], v[30:33], v[22:25], v[38:41]
	v_subrev_u32_e32 v15, s23, v204
	v_mfma_f32_16x16x32_bf16 v[50:53], v[2:5], v[22:25], v[50:53]
	ds_read_b128 v[22:25], v16
	ds_read_b128 v[222:225], v16 offset:2048
	ds_read_b128 v[226:229], v16 offset:4096
	ds_read_b128 v[230:233], v16 offset:6144
	ds_read_b128 v[234:237], v14 offset:32768
	ds_read_b128 v[238:241], v14 offset:34816
	ds_read_b128 v[242:245], v14 offset:36864
	ds_read_b128 v[246:249], v14 offset:38912
	v_mfma_f32_16x16x32_bf16 v[90:93], v[30:33], v[18:21], v[90:93]
	v_mfma_f32_16x16x32_bf16 v[86:89], v[30:33], v[10:13], v[86:89]
	v_mfma_f32_16x16x32_bf16 v[94:97], v[30:33], v[6:9], v[94:97]
	v_mfma_f32_16x16x32_bf16 v[46:49], v[2:5], v[18:21], v[46:49]
	v_mfma_f32_16x16x32_bf16 v[42:45], v[2:5], v[10:13], v[42:45]
	v_mfma_f32_16x16x32_bf16 v[34:37], v[2:5], v[6:9], v[34:37]
	s_add_i32 s20, s6, 4
	s_mul_i32 s23, s20, 0xab
	s_bfe_u32 s23, s23, 0x70009
	s_mul_i32 s23, s23, 3
	s_sub_i32 s20, s20, s23
	s_and_b32 s20, s20, 0xff
	s_mul_i32 s20, s20, 0xc000
	s_waitcnt vmcnt(6)
	v_add_u32_e32 v2, v191, v15
	v_add_u32_e32 v6, v191, v252
	s_waitcnt lgkmcnt(0)
	v_mfma_f32_16x16x32_bf16 v[82:85], v[222:225], v[234:237], v[82:85]
	s_add_i32 s23, s20, s11
	s_waitcnt lgkmcnt(0)
	s_barrier
	v_mfma_f32_16x16x32_bf16 v[78:81], v[222:225], v[238:241], v[78:81]
	ds_read_b128 v[30:33], v2
	ds_read_b128 v[26:29], v2 offset:2048
	ds_read_b128 v[14:17], v2 offset:4096
	ds_read_b128 v[2:5], v2 offset:6144
	v_add_u32_e32 v7, v191, v251
	v_mfma_f32_16x16x32_bf16 v[74:77], v[222:225], v[242:245], v[74:77]
	s_mov_b32 m0, s23
	s_mov_b64 s[34:35], 0x180
	s_add_i32 s20, s20, s12
	v_mfma_f32_16x16x32_bf16 v[70:73], v[222:225], v[246:249], v[70:73]
	v_lshl_add_u64 v[222:223], v[118:119], 0, v[102:103]
	v_lshl_add_u64 v[224:225], v[222:223], 0, s[84:85]
	s_add_i32 s19, s19, 1
	v_mfma_f32_16x16x32_bf16 v[38:41], v[22:25], v[234:237], v[38:41]
	v_mfma_f32_16x16x32_bf16 v[90:93], v[22:25], v[238:241], v[90:93]
	v_mfma_f32_16x16x32_bf16 v[86:89], v[22:25], v[242:245], v[86:89]
	v_mfma_f32_16x16x32_bf16 v[94:97], v[22:25], v[246:249], v[94:97]
	ds_read_b128 v[22:25], v6
	ds_read_b128 v[18:21], v7
	v_add_u32_e32 v6, v191, v250
	ds_read_b128 v[10:13], v6
	ds_read_b128 v[6:9], v6 offset:2048
	global_load_lds_dwordx4 v[224:225], off sc1
	v_lshl_add_u64 v[224:225], v[222:223], 0, s[76:77]
	s_add_i32 m0, s23, 0x400
	v_mfma_f32_16x16x32_bf16 v[66:69], v[226:229], v[234:237], v[66:69]
	global_load_lds_dwordx4 v[224:225], off sc1
	v_lshl_add_u64 v[224:225], v[222:223], 0, s[54:55]
	s_add_i32 m0, s23, 0x800
	v_lshl_add_u64 v[222:223], v[222:223], 0, s[68:69]
	global_load_lds_dwordx4 v[224:225], off sc1
	s_add_i32 m0, s23, 0xc00
	v_mfma_f32_16x16x32_bf16 v[62:65], v[226:229], v[238:241], v[62:65]
	global_load_lds_dwordx4 v[222:223], off sc1
	v_lshl_add_u64 v[222:223], v[120:121], 0, v[102:103]
	v_lshl_add_u64 v[224:225], v[222:223], 0, s[34:35]
	s_add_i32 m0, s20, 0x8000
	s_mov_b64 s[34:35], 0x4180
	global_load_lds_dwordx4 v[224:225], off sc1
	v_lshl_add_u64 v[222:223], v[222:223], 0, s[34:35]
	s_add_i32 m0, s20, 0x8400
	v_mfma_f32_16x16x32_bf16 v[58:61], v[226:229], v[242:245], v[58:61]
	global_load_lds_dwordx4 v[222:223], off sc1
	v_mfma_f32_16x16x32_bf16 v[54:57], v[226:229], v[246:249], v[54:57]
	v_mfma_f32_16x16x32_bf16 v[50:53], v[230:233], v[234:237], v[50:53]
	v_mfma_f32_16x16x32_bf16 v[46:49], v[230:233], v[238:241], v[46:49]
	v_mfma_f32_16x16x32_bf16 v[42:45], v[230:233], v[242:245], v[42:45]
	v_mfma_f32_16x16x32_bf16 v[34:37], v[230:233], v[246:249], v[34:37]
	s_add_i32 s6, s6, 1
	s_add_i32 s13, s13, 0xc000
	s_add_i32 s14, s14, 1
	s_mov_b32 s34, 0xfffff880
	s_mov_b32 s35, -1
	s_cmp_eq_u32 s19, s64
	s_cselect_b64 s[34:35], s[34:35], s[2:3]
	v_lshl_add_u64 v[118:119], v[118:119], 0, s[34:35]
	v_lshl_add_u64 v[120:121], v[120:121], 0, s[34:35]
	s_cmp_eq_u32 s13, 0x9c000
	s_cbranch_scc0 .LBB0_347
	s_waitcnt lgkmcnt(0)
	v_mfma_f32_16x16x32_bf16 v[38:41], v[30:33], v[22:25], v[38:41]
	v_mfma_f32_16x16x32_bf16 v[90:93], v[30:33], v[18:21], v[90:93]
	v_mfma_f32_16x16x32_bf16 v[86:89], v[30:33], v[10:13], v[86:89]
	v_mfma_f32_16x16x32_bf16 v[30:33], v[30:33], v[6:9], v[94:97]
	v_mfma_f32_16x16x32_bf16 v[82:85], v[26:29], v[22:25], v[82:85]
	v_mfma_f32_16x16x32_bf16 v[78:81], v[26:29], v[18:21], v[78:81]
	v_mfma_f32_16x16x32_bf16 v[74:77], v[26:29], v[10:13], v[74:77]
	v_mfma_f32_16x16x32_bf16 v[26:29], v[26:29], v[6:9], v[70:73]
	v_mfma_f32_16x16x32_bf16 v[66:69], v[14:17], v[22:25], v[66:69]
	v_mfma_f32_16x16x32_bf16 v[62:65], v[14:17], v[18:21], v[62:65]
	v_mfma_f32_16x16x32_bf16 v[58:61], v[14:17], v[10:13], v[58:61]
	v_mfma_f32_16x16x32_bf16 v[14:17], v[14:17], v[6:9], v[54:57]
	v_mfma_f32_16x16x32_bf16 v[22:25], v[2:5], v[22:25], v[50:53]
	v_mfma_f32_16x16x32_bf16 v[18:21], v[2:5], v[18:21], v[46:49]
	s_nop 2
	ds_read_b128 v[46:49], v205
	ds_read_b128 v[50:53], v206 offset:2048
	ds_read_b128 v[54:57], v206 offset:4096
	ds_read_b128 v[70:73], v206 offset:6144
	v_mfma_f32_16x16x32_bf16 v[10:13], v[2:5], v[10:13], v[42:45]
	s_nop 2
	ds_read_b128 v[42:45], v207 offset:32768
	ds_read_b128 v[94:97], v208 offset:34816
	ds_read_b128 v[118:121], v208 offset:36864
	ds_read_b128 v[222:225], v208 offset:38912
	v_mfma_f32_16x16x32_bf16 v[2:5], v[2:5], v[6:9], v[34:37]
	s_waitcnt lgkmcnt(0)
	v_mfma_f32_16x16x32_bf16 v[6:9], v[46:49], v[42:45], v[38:41]
	s_waitcnt vmcnt(6)
	s_waitcnt lgkmcnt(0)
	s_barrier
	v_mfma_f32_16x16x32_bf16 v[34:37], v[46:49], v[94:97], v[90:93]
	v_mfma_f32_16x16x32_bf16 v[38:41], v[46:49], v[118:121], v[86:89]
	s_nop 1
	v_add_u32_e32 v90, 0x20800, v212
	v_mfma_f32_16x16x32_bf16 v[30:33], v[46:49], v[222:225], v[30:33]
	v_mfma_f32_16x16x32_bf16 v[46:49], v[50:53], v[42:45], v[82:85]
	v_mfma_f32_16x16x32_bf16 v[78:81], v[50:53], v[94:97], v[78:81]
	v_mfma_f32_16x16x32_bf16 v[74:77], v[50:53], v[118:121], v[74:77]
	v_mfma_f32_16x16x32_bf16 v[26:29], v[50:53], v[222:225], v[26:29]
	v_mfma_f32_16x16x32_bf16 v[50:53], v[54:57], v[42:45], v[66:69]
	v_mfma_f32_16x16x32_bf16 v[62:65], v[54:57], v[94:97], v[62:65]
	v_mfma_f32_16x16x32_bf16 v[58:61], v[54:57], v[118:121], v[58:61]
	v_mfma_f32_16x16x32_bf16 v[14:17], v[54:57], v[222:225], v[14:17]
	v_add_u32_e32 v54, v180, v124
	ds_read_b128 v[54:57], v54
	ds_read_b128 v[66:69], v209 offset:2048
	v_mfma_f32_16x16x32_bf16 v[18:21], v[70:73], v[94:97], v[18:21]
	v_add_u32_e32 v94, 0x21000, v212
	v_mfma_f32_16x16x32_bf16 v[10:13], v[70:73], v[118:121], v[10:13]
	v_add_u32_e32 v118, 0x21800, v212
	v_mfma_f32_16x16x32_bf16 v[22:25], v[70:73], v[42:45], v[22:25]
	ds_read_b128 v[42:45], v209 offset:4096
	ds_read_b128 v[82:85], v209 offset:6144
	ds_read_b128 v[86:89], v211
	ds_read_b128 v[90:93], v90
	ds_read_b128 v[94:97], v94
	ds_read_b128 v[118:121], v118
	v_mfma_f32_16x16x32_bf16 v[2:5], v[70:73], v[222:225], v[2:5]
	s_waitcnt lgkmcnt(0)
	v_mfma_f32_16x16x32_bf16 v[50:53], v[42:45], v[86:89], v[50:53]
	v_mfma_f32_16x16x32_bf16 v[62:65], v[42:45], v[90:93], v[62:65]
	v_mfma_f32_16x16x32_bf16 v[58:61], v[42:45], v[94:97], v[58:61]
	v_mfma_f32_16x16x32_bf16 v[14:17], v[42:45], v[118:121], v[14:17]
	v_add_u32_e32 v42, v180, v128
	v_mfma_f32_16x16x32_bf16 v[6:9], v[54:57], v[86:89], v[6:9]
	v_mfma_f32_16x16x32_bf16 v[34:37], v[54:57], v[90:93], v[34:37]
	v_mfma_f32_16x16x32_bf16 v[38:41], v[54:57], v[94:97], v[38:41]
	v_mfma_f32_16x16x32_bf16 v[30:33], v[54:57], v[118:121], v[30:33]
	v_mfma_f32_16x16x32_bf16 v[46:49], v[66:69], v[86:89], v[46:49]
	v_mfma_f32_16x16x32_bf16 v[54:57], v[66:69], v[90:93], v[78:81]
	v_mfma_f32_16x16x32_bf16 v[70:73], v[66:69], v[94:97], v[74:77]
	v_mfma_f32_16x16x32_bf16 v[26:29], v[66:69], v[118:121], v[26:29]
	ds_read_b128 v[42:45], v42
	ds_read_b128 v[66:69], v213
	ds_read_b128 v[74:77], v214
	ds_read_b128 v[78:81], v215
	v_mfma_f32_16x16x32_bf16 v[22:25], v[82:85], v[86:89], v[22:25]
	v_mfma_f32_16x16x32_bf16 v[18:21], v[82:85], v[90:93], v[18:21]
	v_mfma_f32_16x16x32_bf16 v[10:13], v[82:85], v[94:97], v[10:13]
	ds_read_b128 v[86:89], v216
	ds_read_b128 v[90:93], v217
	ds_read_b128 v[94:97], v218
	ds_read_b128 v[222:225], v219
	v_mfma_f32_16x16x32_bf16 v[2:5], v[82:85], v[118:121], v[2:5]
	s_waitcnt vmcnt(0)
	s_waitcnt lgkmcnt(0)
	v_mfma_f32_16x16x32_bf16 v[6:9], v[42:45], v[86:89], v[6:9]
	s_waitcnt lgkmcnt(0)
	s_barrier
	v_mfma_f32_16x16x32_bf16 v[34:37], v[42:45], v[90:93], v[34:37]
	v_mfma_f32_16x16x32_bf16 v[38:41], v[42:45], v[94:97], v[38:41]
	v_mfma_f32_16x16x32_bf16 v[30:33], v[42:45], v[222:225], v[30:33]
	v_mfma_f32_16x16x32_bf16 v[42:45], v[66:69], v[86:89], v[46:49]
	v_mfma_f32_16x16x32_bf16 v[46:49], v[66:69], v[90:93], v[54:57]
	v_mfma_f32_16x16x32_bf16 v[54:57], v[66:69], v[94:97], v[70:73]
	v_mfma_f32_16x16x32_bf16 v[26:29], v[66:69], v[222:225], v[26:29]
	v_mfma_f32_16x16x32_bf16 v[50:53], v[74:77], v[86:89], v[50:53]
	v_mfma_f32_16x16x32_bf16 v[62:65], v[74:77], v[90:93], v[62:65]
	v_mfma_f32_16x16x32_bf16 v[58:61], v[74:77], v[94:97], v[58:61]
	v_mfma_f32_16x16x32_bf16 v[14:17], v[74:77], v[222:225], v[14:17]
	ds_read_b128 v[66:69], v212 offset:38912
	ds_read_b128 v[70:73], v212 offset:36864
	ds_read_b128 v[74:77], v212 offset:34816
	ds_read_b128 v[82:85], v210 offset:32768
	v_mfma_f32_16x16x32_bf16 v[22:25], v[78:81], v[86:89], v[22:25]
	v_mfma_f32_16x16x32_bf16 v[18:21], v[78:81], v[90:93], v[18:21]
	v_mfma_f32_16x16x32_bf16 v[10:13], v[78:81], v[94:97], v[10:13]
	ds_read_b128 v[86:89], v221 offset:6144
	ds_read_b128 v[90:93], v221 offset:4096
	ds_read_b128 v[94:97], v221 offset:2048
	ds_read_b128 v[118:121], v117
	v_mfma_f32_16x16x32_bf16 v[2:5], v[78:81], v[222:225], v[2:5]
	s_waitcnt lgkmcnt(0)
	v_mfma_f32_16x16x32_bf16 v[42:45], v[94:97], v[82:85], v[42:45]
	v_add_u32_e32 v78, v123, v128
	v_add_u32_e32 v117, v127, v128
	v_mfma_f32_16x16x32_bf16 v[46:49], v[94:97], v[74:77], v[46:49]
	v_mfma_f32_16x16x32_bf16 v[54:57], v[94:97], v[70:73], v[54:57]
	v_mfma_f32_16x16x32_bf16 v[26:29], v[94:97], v[66:69], v[26:29]
	v_add_u32_e32 v94, v126, v128
	v_mfma_f32_16x16x32_bf16 v[50:53], v[90:93], v[82:85], v[50:53]
	v_mfma_f32_16x16x32_bf16 v[62:65], v[90:93], v[74:77], v[62:65]
	v_mfma_f32_16x16x32_bf16 v[58:61], v[90:93], v[70:73], v[58:61]
	v_mfma_f32_16x16x32_bf16 v[14:17], v[90:93], v[66:69], v[14:17]
	v_add_u32_e32 v90, v125, v128
	v_mfma_f32_16x16x32_bf16 v[6:9], v[118:121], v[82:85], v[6:9]
	v_mfma_f32_16x16x32_bf16 v[34:37], v[118:121], v[74:77], v[34:37]
	v_mfma_f32_16x16x32_bf16 v[38:41], v[118:121], v[70:73], v[38:41]
	v_mfma_f32_16x16x32_bf16 v[30:33], v[118:121], v[66:69], v[30:33]
	v_mfma_f32_16x16x32_bf16 v[22:25], v[86:89], v[82:85], v[22:25]
	ds_read_b128 v[78:81], v78
	ds_read_b128 v[82:85], v90 offset:2048
	v_mfma_f32_16x16x32_bf16 v[18:21], v[86:89], v[74:77], v[18:21]
	ds_read_b128 v[74:77], v90 offset:4096
	ds_read_b128 v[90:93], v90 offset:6144
	v_mfma_f32_16x16x32_bf16 v[10:13], v[86:89], v[70:73], v[10:13]
	ds_read_b128 v[70:73], v94 offset:32768
	ds_read_b128 v[94:97], v117 offset:34816
	ds_read_b128 v[118:121], v117 offset:36864
	ds_read_b128 v[222:225], v117 offset:38912
	v_mfma_f32_16x16x32_bf16 v[2:5], v[86:89], v[66:69], v[2:5]
	s_waitcnt vmcnt(0)
	s_waitcnt lgkmcnt(0)
	s_waitcnt lgkmcnt(0)
	v_mfma_f32_16x16x32_bf16 v[6:9], v[78:81], v[70:73], v[6:9]
	s_barrier
	v_mfma_f32_16x16x32_bf16 v[34:37], v[78:81], v[94:97], v[34:37]
	v_mfma_f32_16x16x32_bf16 v[38:41], v[78:81], v[118:121], v[38:41]
	v_mfma_f32_16x16x32_bf16 v[30:33], v[78:81], v[222:225], v[30:33]
	v_mfma_f32_16x16x32_bf16 v[42:45], v[82:85], v[70:73], v[42:45]
	v_mfma_f32_16x16x32_bf16 v[46:49], v[82:85], v[94:97], v[46:49]
	v_mfma_f32_16x16x32_bf16 v[54:57], v[82:85], v[118:121], v[54:57]
	v_mfma_f32_16x16x32_bf16 v[26:29], v[82:85], v[222:225], v[26:29]
	v_mfma_f32_16x16x32_bf16 v[50:53], v[74:77], v[70:73], v[50:53]
	v_mfma_f32_16x16x32_bf16 v[62:65], v[74:77], v[94:97], v[62:65]
	v_mfma_f32_16x16x32_bf16 v[58:61], v[74:77], v[118:121], v[58:61]
	v_mfma_f32_16x16x32_bf16 v[14:17], v[74:77], v[222:225], v[14:17]
	v_mfma_f32_16x16x32_bf16 v[22:25], v[90:93], v[70:73], v[22:25]
	v_mfma_f32_16x16x32_bf16 v[18:21], v[90:93], v[94:97], v[18:21]
	v_mfma_f32_16x16x32_bf16 v[10:13], v[90:93], v[118:121], v[10:13]
	v_mfma_f32_16x16x32_bf16 v[2:5], v[90:93], v[222:225], v[2:5]
	s_waitcnt lgkmcnt(0)
	s_barrier
	s_mov_b32 s67, 0
	v_readlane_b32 s64, v255, 40
	s_cmp_eq_u32 s64, 0
	s_cbranch_scc1 .Lip_noasync
	v_readlane_b32 s65, v255, 57
	s_add_i32 s65, s75, s65
	s_cmpk_gt_i32 s65, 0x287
	s_cbranch_scc1 .Lip_noasync
	s_mul_hi_i32 s46, s65, 0x2aaaaaab
	s_lshr_b32 s47, s46, 31
	s_ashr_i32 s46, s46, 2
	s_add_i32 s46, s46, s47
	s_mul_i32 s46, s46, 24
	s_sub_i32 s65, s65, s46
	s_lshl_b32 s65, s65, 7
	v_and_b32_e32 v246, 7, v137
	v_lshlrev_b32_e32 v246, 4, v246
	v_add_u32_e32 v246, s65, v246
	s_add_u32 s46, s94, 0xcbcc000
	s_addc_u32 s47, s95, 0
	global_load_dwordx4 v[242:245], v246, s[46:47] sc1
	s_mov_b32 s67, 1
